# P6 epilogue: the seven later row sum-of-squares loads issued behind slice 0's, per-slice vmcnt(0) waits removed
# speedup vs baseline: 1.0082x; 1.0010x over previous
.LBB0_645:
	s_lshl_b32 s9, s10, 8
	v_readlane_b32 s10, v254, 60
	s_add_i32 s9, s9, s10
	v_or_b32_e32 v172, s9, v1
	v_ashrrev_i32_e32 v173, 31, v172
	v_lshl_add_u64 v[174:175], v[172:173], 2, s[0:1]
	global_load_dword v130, v[174:175], off
	global_load_dword v220, v[174:175], off offset:64
	global_load_dword v221, v[174:175], off offset:128
	global_load_dword v222, v[174:175], off offset:192
	global_load_dword v223, v[174:175], off offset:512
	global_load_dword v224, v[174:175], off offset:576
	global_load_dword v225, v[174:175], off offset:640
	global_load_dword v226, v[174:175], off offset:704
	s_cmp_lg_u32 s8, 0
	s_cselect_b64 s[90:91], -1, 0
	s_cmp_gt_i32 s8, 2
	s_cselect_b64 s[92:93], -1, 0
	s_cmp_gt_u32 s8, 6
	s_cselect_b64 s[84:85], -1, 0
	s_cmp_eq_u32 s8, 6
	s_cselect_b64 s[68:69], -1, 0
	s_cmp_lg_u32 s8, 6
	s_cselect_b64 s[82:83], -1, 0
	s_lshl_b32 s10, s8, 8
	v_readlane_b32 s11, v254, 63
	s_add_i32 s16, s11, s10
	s_cmp_eq_u32 s8, 1
	s_cselect_b64 s[66:67], -1, 0
	s_lshl_b32 s64, s8, 6
	s_ashr_i32 s8, s9, 6
	s_ashr_i32 s9, s8, 31
	s_ashr_i32 s65, s64, 31
	s_lshl_b64 s[88:89], s[8:9], 13
	s_add_u32 s8, s8, s74
	s_addc_u32 s9, s9, 0
	s_lshl_b64 s[86:87], s[8:9], 13
	s_mov_b64 s[8:9], -1
	s_and_b64 vcc, exec, s[90:91]
	s_waitcnt vmcnt(0)
	v_fmamk_f32 v130, v130, 0x3a800000, v155
	v_rsq_f32_e32 v176, v130
	s_cbranch_vccz .LBB0_668
	s_and_b64 vcc, exec, s[92:93]
	s_cbranch_vccz .LBB0_662
	s_and_b64 vcc, exec, s[84:85]
	s_cbranch_vccz .LBB0_655
	s_andn2_b64 vcc, exec, s[34:35]
	s_cbranch_vccnz .LBB0_654
	v_readlane_b32 s8, v254, 58
	v_readlane_b32 s9, v254, 59
	s_nop 1
	v_mov_b64_e32 v[130:131], s[8:9]
	s_movk_i32 s8, 0x90
	v_mad_i64_i32 v[130:131], s[8:9], v172, s8, v[130:131]
	s_mov_b64 s[8:9], exec
	v_readlane_b32 s10, v255, 0
	v_readlane_b32 s11, v255, 1
	s_and_b64 s[10:11], s[8:9], s[10:11]
	s_mov_b64 exec, s[10:11]
	s_cbranch_execz .LBB0_651
	global_load_dwordx4 v[246:249], v[160:161], off
	v_lshlrev_b32_e32 v142, 2, v146
	s_waitcnt vmcnt(0)
	v_mov_b32_e32 v132, v246
	v_fmac_f32_e32 v132, v126, v176
	v_mul_f32_e32 v132, 0xbfb8aa3b, v132
	v_exp_f32_e32 v132, v132
	s_nop 0
	v_add_f32_e32 v177, 1.0, v132
	v_div_scale_f32 v178, s[10:11], v177, v177, 1.0
	v_rcp_f32_e32 v179, v178
	v_lshl_add_u64 v[132:133], v[130:131], 0, v[142:143]
	v_div_scale_f32 v142, vcc, 1.0, v177, 1.0
	v_fma_f32 v180, -v178, v179, 1.0
	v_fmac_f32_e32 v179, v180, v179
	v_mul_f32_e32 v180, v142, v179
	v_fma_f32 v181, -v178, v180, v142
	v_fmac_f32_e32 v180, v181, v179
	v_fma_f32 v142, -v178, v180, v142
	v_div_fmas_f32 v142, v142, v179, v180
	v_div_fixup_f32 v142, v142, v177, 1.0
	global_store_dword v[132:133], v142, off
	v_mov_b32_e32 v142, v247
	v_fmac_f32_e32 v142, v127, v176
	v_mul_f32_e32 v142, 0xbfb8aa3b, v142
	v_exp_f32_e32 v142, v142
	s_nop 0
	v_add_f32_e32 v142, 1.0, v142
	v_div_scale_f32 v177, s[10:11], v142, v142, 1.0
	v_rcp_f32_e32 v178, v177
	v_div_scale_f32 v179, vcc, 1.0, v142, 1.0
	v_fma_f32 v180, -v177, v178, 1.0
	v_fmac_f32_e32 v178, v180, v178
	v_mul_f32_e32 v180, v179, v178
	v_fma_f32 v181, -v177, v180, v179
	v_fmac_f32_e32 v180, v181, v178
	v_fma_f32 v177, -v177, v180, v179
	v_div_fmas_f32 v177, v177, v178, v180
	v_div_fixup_f32 v142, v177, v142, 1.0
	global_store_dword v[132:133], v142, off offset:4
	v_mov_b32_e32 v142, v248
	v_fmac_f32_e32 v142, v128, v176
	v_mul_f32_e32 v142, 0xbfb8aa3b, v142
	v_exp_f32_e32 v142, v142
	s_nop 0
	v_add_f32_e32 v142, 1.0, v142
	v_div_scale_f32 v177, s[10:11], v142, v142, 1.0
	v_rcp_f32_e32 v178, v177
	v_div_scale_f32 v179, vcc, 1.0, v142, 1.0
	v_fma_f32 v180, -v177, v178, 1.0
	v_fmac_f32_e32 v178, v180, v178
	v_mul_f32_e32 v180, v179, v178
	v_fma_f32 v181, -v177, v180, v179
	v_fmac_f32_e32 v180, v181, v178
	v_fma_f32 v177, -v177, v180, v179
	v_div_fmas_f32 v177, v177, v178, v180
	v_div_fixup_f32 v142, v177, v142, 1.0
	global_store_dword v[132:133], v142, off offset:8
	v_mov_b32_e32 v142, v249
	v_fmac_f32_e32 v142, v129, v176
	v_mul_f32_e32 v142, 0xbfb8aa3b, v142
	v_exp_f32_e32 v142, v142
	s_nop 0
	v_add_f32_e32 v142, 1.0, v142
	v_div_scale_f32 v177, s[10:11], v142, v142, 1.0
	v_rcp_f32_e32 v178, v177
	v_div_scale_f32 v179, vcc, 1.0, v142, 1.0
	v_fma_f32 v180, -v177, v178, 1.0
	v_fmac_f32_e32 v178, v180, v178
	v_mul_f32_e32 v180, v179, v178
	v_fma_f32 v181, -v177, v180, v179
	v_fmac_f32_e32 v180, v181, v178
	v_fma_f32 v177, -v177, v180, v179
	v_div_fmas_f32 v177, v177, v178, v180
	v_div_fixup_f32 v142, v177, v142, 1.0
	global_store_dword v[132:133], v142, off offset:12

.LBB0_670:
	v_or_b32_e32 v120, 16, v172
	v_ashrrev_i32_e32 v121, 31, v120
	v_lshl_add_u64 v[114:115], v[120:121], 2, s[0:1]
	s_nop 1
	v_mov_b32_e32 v114, v220
	v_cndmask_b32_e64 v115, 0, 1, s[90:91]
	v_cmp_ne_u32_e64 s[10:11], 1, v115
	s_andn2_b64 vcc, exec, s[90:91]
	v_fmamk_f32 v114, v114, 0x3a800000, v155
	v_rsq_f32_e32 v118, v114
	v_cndmask_b32_e64 v114, 0, 1, s[92:93]
	v_cmp_ne_u32_e64 s[8:9], 1, v114
	s_cbranch_vccnz .LBB0_841
	s_and_b64 vcc, exec, s[8:9]
	s_mov_b64 s[12:13], -1
	s_cbranch_vccnz .LBB0_687
	s_andn2_b64 vcc, exec, s[84:85]
	s_cbranch_vccnz .LBB0_680
	s_andn2_b64 vcc, exec, s[34:35]
	s_cbranch_vccnz .LBB0_679
	v_readlane_b32 s12, v254, 58
	v_readlane_b32 s13, v254, 59
	v_readlane_b32 s44, v255, 0
	v_readlane_b32 s45, v255, 1
	v_mov_b64_e32 v[114:115], s[12:13]
	s_movk_i32 s12, 0x90
	v_mad_i64_i32 v[114:115], s[12:13], v120, s12, v[114:115]
	s_and_saveexec_b64 s[12:13], s[44:45]
	s_cbranch_execz .LBB0_676
	v_mov_b32_e32 v116, v246
	v_lshlrev_b32_e32 v142, 2, v146
	v_fmac_f32_e32 v116, v110, v118
	v_mul_f32_e32 v116, 0xbfb8aa3b, v116
	v_exp_f32_e32 v116, v116
	s_nop 0
	v_add_f32_e32 v119, 1.0, v116
	v_div_scale_f32 v122, s[90:91], v119, v119, 1.0
	v_rcp_f32_e32 v123, v122
	v_div_scale_f32 v124, vcc, 1.0, v119, 1.0
	v_lshl_add_u64 v[116:117], v[114:115], 0, v[142:143]
	v_fma_f32 v125, -v122, v123, 1.0
	v_fmac_f32_e32 v123, v125, v123
	v_mul_f32_e32 v125, v124, v123
	v_fma_f32 v126, -v122, v125, v124
	v_fmac_f32_e32 v125, v126, v123
	v_fma_f32 v122, -v122, v125, v124
	v_div_fmas_f32 v122, v122, v123, v125
	v_div_fixup_f32 v119, v122, v119, 1.0
	global_store_dword v[116:117], v119, off
	v_mov_b32_e32 v119, v247
	v_fmac_f32_e32 v119, v111, v118
	v_mul_f32_e32 v119, 0xbfb8aa3b, v119
	v_exp_f32_e32 v119, v119
	s_nop 0
	v_add_f32_e32 v119, 1.0, v119
	v_div_scale_f32 v122, s[90:91], v119, v119, 1.0
	v_rcp_f32_e32 v123, v122
	v_div_scale_f32 v124, vcc, 1.0, v119, 1.0
	v_fma_f32 v125, -v122, v123, 1.0
	v_fmac_f32_e32 v123, v125, v123
	v_mul_f32_e32 v125, v124, v123
	v_fma_f32 v126, -v122, v125, v124
	v_fmac_f32_e32 v125, v126, v123
	v_fma_f32 v122, -v122, v125, v124
	v_div_fmas_f32 v122, v122, v123, v125
	v_div_fixup_f32 v119, v122, v119, 1.0
	global_store_dword v[116:117], v119, off offset:4
	v_mov_b32_e32 v119, v248
	v_fmac_f32_e32 v119, v112, v118
	v_mul_f32_e32 v119, 0xbfb8aa3b, v119
	v_exp_f32_e32 v119, v119
	s_nop 0
	v_add_f32_e32 v119, 1.0, v119
	v_div_scale_f32 v122, s[90:91], v119, v119, 1.0
	v_rcp_f32_e32 v123, v122
	v_div_scale_f32 v124, vcc, 1.0, v119, 1.0
	v_fma_f32 v125, -v122, v123, 1.0
	v_fmac_f32_e32 v123, v125, v123
	v_mul_f32_e32 v125, v124, v123
	v_fma_f32 v126, -v122, v125, v124
	v_fmac_f32_e32 v125, v126, v123
	v_fma_f32 v122, -v122, v125, v124
	v_div_fmas_f32 v122, v122, v123, v125
	v_div_fixup_f32 v119, v122, v119, 1.0
	global_store_dword v[116:117], v119, off offset:8
	v_mov_b32_e32 v119, v249
	v_fmac_f32_e32 v119, v113, v118
	v_mul_f32_e32 v119, 0xbfb8aa3b, v119
	v_exp_f32_e32 v119, v119
	s_nop 0
	v_add_f32_e32 v119, 1.0, v119
	v_div_scale_f32 v122, s[90:91], v119, v119, 1.0
	v_rcp_f32_e32 v123, v122
	v_div_scale_f32 v124, vcc, 1.0, v119, 1.0
	v_fma_f32 v125, -v122, v123, 1.0
	v_fmac_f32_e32 v123, v125, v123
	v_mul_f32_e32 v125, v124, v123
	v_fma_f32 v126, -v122, v125, v124
	v_fmac_f32_e32 v125, v126, v123
	v_fma_f32 v122, -v122, v125, v124
	v_div_fmas_f32 v122, v122, v123, v125
	v_div_fixup_f32 v119, v122, v119, 1.0
	global_store_dword v[116:117], v119, off offset:12

.LBB0_694:
	v_or_b32_e32 v104, 32, v172
	v_ashrrev_i32_e32 v105, 31, v104
	v_lshl_add_u64 v[98:99], v[104:105], 2, s[0:1]
	s_nop 1
	v_mov_b32_e32 v98, v221
	s_and_b64 vcc, exec, s[10:11]
	v_fmamk_f32 v98, v98, 0x3a800000, v155
	v_rsq_f32_e32 v102, v98
	s_cbranch_vccnz .LBB0_842
	s_and_b64 vcc, exec, s[8:9]
	s_mov_b64 s[12:13], -1
	s_cbranch_vccnz .LBB0_711
	s_andn2_b64 vcc, exec, s[84:85]
	s_cbranch_vccnz .LBB0_704
	s_andn2_b64 vcc, exec, s[34:35]
	s_cbranch_vccnz .LBB0_703
	v_readlane_b32 s12, v254, 58
	v_readlane_b32 s13, v254, 59
	v_readlane_b32 s44, v255, 0
	v_readlane_b32 s45, v255, 1
	v_mov_b64_e32 v[98:99], s[12:13]
	s_movk_i32 s12, 0x90
	v_mad_i64_i32 v[98:99], s[12:13], v104, s12, v[98:99]
	s_and_saveexec_b64 s[12:13], s[44:45]
	s_cbranch_execz .LBB0_700
	v_mov_b32_e32 v100, v246
	v_lshlrev_b32_e32 v142, 2, v146
	v_fmac_f32_e32 v100, v94, v102
	v_mul_f32_e32 v100, 0xbfb8aa3b, v100
	v_exp_f32_e32 v100, v100
	s_nop 0
	v_add_f32_e32 v103, 1.0, v100
	v_div_scale_f32 v106, s[90:91], v103, v103, 1.0
	v_rcp_f32_e32 v107, v106
	v_div_scale_f32 v108, vcc, 1.0, v103, 1.0
	v_lshl_add_u64 v[100:101], v[98:99], 0, v[142:143]
	v_fma_f32 v109, -v106, v107, 1.0
	v_fmac_f32_e32 v107, v109, v107
	v_mul_f32_e32 v109, v108, v107
	v_fma_f32 v110, -v106, v109, v108
	v_fmac_f32_e32 v109, v110, v107
	v_fma_f32 v106, -v106, v109, v108
	v_div_fmas_f32 v106, v106, v107, v109
	v_div_fixup_f32 v103, v106, v103, 1.0
	global_store_dword v[100:101], v103, off
	v_mov_b32_e32 v103, v247
	v_fmac_f32_e32 v103, v95, v102
	v_mul_f32_e32 v103, 0xbfb8aa3b, v103
	v_exp_f32_e32 v103, v103
	s_nop 0
	v_add_f32_e32 v103, 1.0, v103
	v_div_scale_f32 v106, s[90:91], v103, v103, 1.0
	v_rcp_f32_e32 v107, v106
	v_div_scale_f32 v108, vcc, 1.0, v103, 1.0
	v_fma_f32 v109, -v106, v107, 1.0
	v_fmac_f32_e32 v107, v109, v107
	v_mul_f32_e32 v109, v108, v107
	v_fma_f32 v110, -v106, v109, v108
	v_fmac_f32_e32 v109, v110, v107
	v_fma_f32 v106, -v106, v109, v108
	v_div_fmas_f32 v106, v106, v107, v109
	v_div_fixup_f32 v103, v106, v103, 1.0
	global_store_dword v[100:101], v103, off offset:4
	v_mov_b32_e32 v103, v248
	v_fmac_f32_e32 v103, v96, v102
	v_mul_f32_e32 v103, 0xbfb8aa3b, v103
	v_exp_f32_e32 v103, v103
	s_nop 0
	v_add_f32_e32 v103, 1.0, v103
	v_div_scale_f32 v106, s[90:91], v103, v103, 1.0
	v_rcp_f32_e32 v107, v106
	v_div_scale_f32 v108, vcc, 1.0, v103, 1.0
	v_fma_f32 v109, -v106, v107, 1.0
	v_fmac_f32_e32 v107, v109, v107
	v_mul_f32_e32 v109, v108, v107
	v_fma_f32 v110, -v106, v109, v108
	v_fmac_f32_e32 v109, v110, v107
	v_fma_f32 v106, -v106, v109, v108
	v_div_fmas_f32 v106, v106, v107, v109
	v_div_fixup_f32 v103, v106, v103, 1.0
	global_store_dword v[100:101], v103, off offset:8
	v_mov_b32_e32 v103, v249
	v_fmac_f32_e32 v103, v97, v102
	v_mul_f32_e32 v103, 0xbfb8aa3b, v103
	v_exp_f32_e32 v103, v103
	s_nop 0
	v_add_f32_e32 v103, 1.0, v103
	v_div_scale_f32 v106, s[90:91], v103, v103, 1.0
	v_rcp_f32_e32 v107, v106
	v_div_scale_f32 v108, vcc, 1.0, v103, 1.0
	v_fma_f32 v109, -v106, v107, 1.0
	v_fmac_f32_e32 v107, v109, v107
	v_mul_f32_e32 v109, v108, v107
	v_fma_f32 v110, -v106, v109, v108
	v_fmac_f32_e32 v109, v110, v107
	v_fma_f32 v106, -v106, v109, v108
	v_div_fmas_f32 v106, v106, v107, v109
	v_div_fixup_f32 v103, v106, v103, 1.0
	global_store_dword v[100:101], v103, off offset:12

.LBB0_718:
	v_or_b32_e32 v88, 48, v172
	v_ashrrev_i32_e32 v89, 31, v88
	v_lshl_add_u64 v[82:83], v[88:89], 2, s[0:1]
	s_nop 1
	v_mov_b32_e32 v82, v222
	s_and_b64 vcc, exec, s[10:11]
	v_fmamk_f32 v82, v82, 0x3a800000, v155
	v_rsq_f32_e32 v86, v82
	s_cbranch_vccnz .LBB0_843
	s_and_b64 vcc, exec, s[8:9]
	s_mov_b64 s[12:13], -1
	s_cbranch_vccnz .LBB0_735
	s_andn2_b64 vcc, exec, s[84:85]
	s_cbranch_vccnz .LBB0_728
	s_andn2_b64 vcc, exec, s[34:35]
	s_cbranch_vccnz .LBB0_727
	v_readlane_b32 s12, v254, 58
	v_readlane_b32 s13, v254, 59
	v_readlane_b32 s44, v255, 0
	v_readlane_b32 s45, v255, 1
	v_mov_b64_e32 v[82:83], s[12:13]
	s_movk_i32 s12, 0x90
	v_mad_i64_i32 v[82:83], s[12:13], v88, s12, v[82:83]
	s_and_saveexec_b64 s[12:13], s[44:45]
	s_cbranch_execz .LBB0_724
	v_mov_b32_e32 v84, v246
	v_lshlrev_b32_e32 v142, 2, v146
	v_fmac_f32_e32 v84, v78, v86
	v_mul_f32_e32 v84, 0xbfb8aa3b, v84
	v_exp_f32_e32 v84, v84
	s_nop 0
	v_add_f32_e32 v87, 1.0, v84
	v_div_scale_f32 v90, s[90:91], v87, v87, 1.0
	v_rcp_f32_e32 v91, v90
	v_div_scale_f32 v92, vcc, 1.0, v87, 1.0
	v_lshl_add_u64 v[84:85], v[82:83], 0, v[142:143]
	v_fma_f32 v93, -v90, v91, 1.0
	v_fmac_f32_e32 v91, v93, v91
	v_mul_f32_e32 v93, v92, v91
	v_fma_f32 v94, -v90, v93, v92
	v_fmac_f32_e32 v93, v94, v91
	v_fma_f32 v90, -v90, v93, v92
	v_div_fmas_f32 v90, v90, v91, v93
	v_div_fixup_f32 v87, v90, v87, 1.0
	global_store_dword v[84:85], v87, off
	v_mov_b32_e32 v87, v247
	v_fmac_f32_e32 v87, v79, v86
	v_mul_f32_e32 v87, 0xbfb8aa3b, v87
	v_exp_f32_e32 v87, v87
	s_nop 0
	v_add_f32_e32 v87, 1.0, v87
	v_div_scale_f32 v90, s[90:91], v87, v87, 1.0
	v_rcp_f32_e32 v91, v90
	v_div_scale_f32 v92, vcc, 1.0, v87, 1.0
	v_fma_f32 v93, -v90, v91, 1.0
	v_fmac_f32_e32 v91, v93, v91
	v_mul_f32_e32 v93, v92, v91
	v_fma_f32 v94, -v90, v93, v92
	v_fmac_f32_e32 v93, v94, v91
	v_fma_f32 v90, -v90, v93, v92
	v_div_fmas_f32 v90, v90, v91, v93
	v_div_fixup_f32 v87, v90, v87, 1.0
	global_store_dword v[84:85], v87, off offset:4
	v_mov_b32_e32 v87, v248
	v_fmac_f32_e32 v87, v80, v86
	v_mul_f32_e32 v87, 0xbfb8aa3b, v87
	v_exp_f32_e32 v87, v87
	s_nop 0
	v_add_f32_e32 v87, 1.0, v87
	v_div_scale_f32 v90, s[90:91], v87, v87, 1.0
	v_rcp_f32_e32 v91, v90
	v_div_scale_f32 v92, vcc, 1.0, v87, 1.0
	v_fma_f32 v93, -v90, v91, 1.0
	v_fmac_f32_e32 v91, v93, v91
	v_mul_f32_e32 v93, v92, v91
	v_fma_f32 v94, -v90, v93, v92
	v_fmac_f32_e32 v93, v94, v91
	v_fma_f32 v90, -v90, v93, v92
	v_div_fmas_f32 v90, v90, v91, v93
	v_div_fixup_f32 v87, v90, v87, 1.0
	global_store_dword v[84:85], v87, off offset:8
	v_mov_b32_e32 v87, v249
	v_fmac_f32_e32 v87, v81, v86
	v_mul_f32_e32 v87, 0xbfb8aa3b, v87
	v_exp_f32_e32 v87, v87
	s_nop 0
	v_add_f32_e32 v87, 1.0, v87
	v_div_scale_f32 v90, s[90:91], v87, v87, 1.0
	v_rcp_f32_e32 v91, v90
	v_div_scale_f32 v92, vcc, 1.0, v87, 1.0
	v_fma_f32 v93, -v90, v91, 1.0
	v_fmac_f32_e32 v91, v93, v91
	v_mul_f32_e32 v93, v92, v91
	v_fma_f32 v94, -v90, v93, v92
	v_fmac_f32_e32 v93, v94, v91
	v_fma_f32 v90, -v90, v93, v92
	v_div_fmas_f32 v90, v90, v91, v93
	v_div_fixup_f32 v87, v90, v87, 1.0
	global_store_dword v[84:85], v87, off offset:12

.LBB0_742:
	s_nop 1
	v_mov_b32_e32 v72, v223
	v_add_u32_e32 v70, 0x80, v172
	v_ashrrev_i32_e32 v66, 6, v70
	v_ashrrev_i32_e32 v67, 31, v66
	v_lshlrev_b64 v[68:69], 13, v[66:67]
	v_lshl_add_u64 v[66:67], v[66:67], 0, s[74:75]
	v_lshlrev_b64 v[66:67], 13, v[66:67]
	v_ashrrev_i32_e32 v71, 31, v70
	s_and_b64 vcc, exec, s[10:11]
	v_fmamk_f32 v72, v72, 0x3a800000, v155
	v_rsq_f32_e32 v72, v72
	s_cbranch_vccnz .LBB0_844
	s_and_b64 vcc, exec, s[8:9]
	s_mov_b64 s[12:13], -1
	s_cbranch_vccnz .LBB0_759
	s_andn2_b64 vcc, exec, s[84:85]
	s_cbranch_vccnz .LBB0_752
	s_andn2_b64 vcc, exec, s[34:35]
	s_cbranch_vccnz .LBB0_751
	v_readlane_b32 s12, v254, 58
	v_readlane_b32 s13, v254, 59
	v_readlane_b32 s44, v255, 0
	v_readlane_b32 s45, v255, 1
	v_mov_b64_e32 v[74:75], s[12:13]
	s_movk_i32 s12, 0x90
	v_mad_i64_i32 v[74:75], s[12:13], v70, s12, v[74:75]
	s_and_saveexec_b64 s[12:13], s[44:45]
	s_cbranch_execz .LBB0_748
	v_mov_b32_e32 v73, v246
	v_lshlrev_b32_e32 v142, 2, v146
	v_lshl_add_u64 v[76:77], v[74:75], 0, v[142:143]
	v_fmac_f32_e32 v73, v62, v72
	v_mul_f32_e32 v73, 0xbfb8aa3b, v73
	v_exp_f32_e32 v73, v73
	s_nop 0
	v_add_f32_e32 v73, 1.0, v73
	v_div_scale_f32 v78, s[86:87], v73, v73, 1.0
	v_rcp_f32_e32 v79, v78
	v_div_scale_f32 v80, vcc, 1.0, v73, 1.0
	v_fma_f32 v81, -v78, v79, 1.0
	v_fmac_f32_e32 v79, v81, v79
	v_mul_f32_e32 v81, v80, v79
	v_fma_f32 v82, -v78, v81, v80
	v_fmac_f32_e32 v81, v82, v79
	v_fma_f32 v78, -v78, v81, v80
	v_div_fmas_f32 v78, v78, v79, v81
	v_div_fixup_f32 v73, v78, v73, 1.0
	global_store_dword v[76:77], v73, off
	v_mov_b32_e32 v73, v247
	v_fmac_f32_e32 v73, v63, v72
	v_mul_f32_e32 v73, 0xbfb8aa3b, v73
	v_exp_f32_e32 v73, v73
	s_nop 0
	v_add_f32_e32 v73, 1.0, v73
	v_div_scale_f32 v78, s[86:87], v73, v73, 1.0
	v_rcp_f32_e32 v79, v78
	v_div_scale_f32 v80, vcc, 1.0, v73, 1.0
	v_fma_f32 v81, -v78, v79, 1.0
	v_fmac_f32_e32 v79, v81, v79
	v_mul_f32_e32 v81, v80, v79
	v_fma_f32 v82, -v78, v81, v80
	v_fmac_f32_e32 v81, v82, v79
	v_fma_f32 v78, -v78, v81, v80
	v_div_fmas_f32 v78, v78, v79, v81
	v_div_fixup_f32 v73, v78, v73, 1.0
	global_store_dword v[76:77], v73, off offset:4
	v_mov_b32_e32 v73, v248
	v_fmac_f32_e32 v73, v64, v72
	v_mul_f32_e32 v73, 0xbfb8aa3b, v73
	v_exp_f32_e32 v73, v73
	s_nop 0
	v_add_f32_e32 v73, 1.0, v73
	v_div_scale_f32 v78, s[86:87], v73, v73, 1.0
	v_rcp_f32_e32 v79, v78
	v_div_scale_f32 v80, vcc, 1.0, v73, 1.0
	v_fma_f32 v81, -v78, v79, 1.0
	v_fmac_f32_e32 v79, v81, v79
	v_mul_f32_e32 v81, v80, v79
	v_fma_f32 v82, -v78, v81, v80
	v_fmac_f32_e32 v81, v82, v79
	v_fma_f32 v78, -v78, v81, v80
	v_div_fmas_f32 v78, v78, v79, v81
	v_div_fixup_f32 v73, v78, v73, 1.0
	global_store_dword v[76:77], v73, off offset:8
	v_mov_b32_e32 v73, v249
	v_fmac_f32_e32 v73, v65, v72
	v_mul_f32_e32 v73, 0xbfb8aa3b, v73
	v_exp_f32_e32 v73, v73
	s_nop 0
	v_add_f32_e32 v73, 1.0, v73
	v_div_scale_f32 v78, s[86:87], v73, v73, 1.0
	v_rcp_f32_e32 v79, v78
	v_div_scale_f32 v80, vcc, 1.0, v73, 1.0
	v_fma_f32 v81, -v78, v79, 1.0
	v_fmac_f32_e32 v79, v81, v79
	v_mul_f32_e32 v81, v80, v79
	v_fma_f32 v82, -v78, v81, v80
	v_fmac_f32_e32 v81, v82, v79
	v_fma_f32 v78, -v78, v81, v80
	v_div_fmas_f32 v78, v78, v79, v81
	v_div_fixup_f32 v73, v78, v73, 1.0
	global_store_dword v[76:77], v73, off offset:12

.LBB0_766:
	s_nop 1
	v_mov_b32_e32 v50, v224
	v_add_u32_e32 v56, 0x90, v172
	s_and_b64 vcc, exec, s[10:11]
	v_ashrrev_i32_e32 v57, 31, v56
	v_fmamk_f32 v50, v50, 0x3a800000, v155
	v_rsq_f32_e32 v54, v50
	s_cbranch_vccnz .LBB0_845
	s_and_b64 vcc, exec, s[8:9]
	s_mov_b64 s[12:13], -1
	s_cbranch_vccnz .LBB0_783
	s_andn2_b64 vcc, exec, s[84:85]
	s_cbranch_vccnz .LBB0_776
	s_andn2_b64 vcc, exec, s[34:35]
	s_cbranch_vccnz .LBB0_775
	v_readlane_b32 s12, v254, 58
	v_readlane_b32 s13, v254, 59
	v_readlane_b32 s44, v255, 0
	v_readlane_b32 s45, v255, 1
	v_mov_b64_e32 v[50:51], s[12:13]
	s_movk_i32 s12, 0x90
	v_mad_i64_i32 v[50:51], s[12:13], v56, s12, v[50:51]
	s_and_saveexec_b64 s[12:13], s[44:45]
	s_cbranch_execz .LBB0_772
	v_mov_b32_e32 v52, v246
	v_lshlrev_b32_e32 v142, 2, v146
	v_fmac_f32_e32 v52, v46, v54
	v_mul_f32_e32 v52, 0xbfb8aa3b, v52
	v_exp_f32_e32 v52, v52
	s_nop 0
	v_add_f32_e32 v55, 1.0, v52
	v_div_scale_f32 v58, s[86:87], v55, v55, 1.0
	v_rcp_f32_e32 v59, v58
	v_div_scale_f32 v60, vcc, 1.0, v55, 1.0
	v_lshl_add_u64 v[52:53], v[50:51], 0, v[142:143]
	v_fma_f32 v61, -v58, v59, 1.0
	v_fmac_f32_e32 v59, v61, v59
	v_mul_f32_e32 v61, v60, v59
	v_fma_f32 v62, -v58, v61, v60
	v_fmac_f32_e32 v61, v62, v59
	v_fma_f32 v58, -v58, v61, v60
	v_div_fmas_f32 v58, v58, v59, v61
	v_div_fixup_f32 v55, v58, v55, 1.0
	global_store_dword v[52:53], v55, off
	v_mov_b32_e32 v55, v247
	v_fmac_f32_e32 v55, v47, v54
	v_mul_f32_e32 v55, 0xbfb8aa3b, v55
	v_exp_f32_e32 v55, v55
	s_nop 0
	v_add_f32_e32 v55, 1.0, v55
	v_div_scale_f32 v58, s[86:87], v55, v55, 1.0
	v_rcp_f32_e32 v59, v58
	v_div_scale_f32 v60, vcc, 1.0, v55, 1.0
	v_fma_f32 v61, -v58, v59, 1.0
	v_fmac_f32_e32 v59, v61, v59
	v_mul_f32_e32 v61, v60, v59
	v_fma_f32 v62, -v58, v61, v60
	v_fmac_f32_e32 v61, v62, v59
	v_fma_f32 v58, -v58, v61, v60
	v_div_fmas_f32 v58, v58, v59, v61
	v_div_fixup_f32 v55, v58, v55, 1.0
	global_store_dword v[52:53], v55, off offset:4
	v_mov_b32_e32 v55, v248
	v_fmac_f32_e32 v55, v48, v54
	v_mul_f32_e32 v55, 0xbfb8aa3b, v55
	v_exp_f32_e32 v55, v55
	s_nop 0
	v_add_f32_e32 v55, 1.0, v55
	v_div_scale_f32 v58, s[86:87], v55, v55, 1.0
	v_rcp_f32_e32 v59, v58
	v_div_scale_f32 v60, vcc, 1.0, v55, 1.0
	v_fma_f32 v61, -v58, v59, 1.0
	v_fmac_f32_e32 v59, v61, v59
	v_mul_f32_e32 v61, v60, v59
	v_fma_f32 v62, -v58, v61, v60
	v_fmac_f32_e32 v61, v62, v59
	v_fma_f32 v58, -v58, v61, v60
	v_div_fmas_f32 v58, v58, v59, v61
	v_div_fixup_f32 v55, v58, v55, 1.0
	global_store_dword v[52:53], v55, off offset:8
	v_mov_b32_e32 v55, v249
	v_fmac_f32_e32 v55, v49, v54
	v_mul_f32_e32 v55, 0xbfb8aa3b, v55
	v_exp_f32_e32 v55, v55
	s_nop 0
	v_add_f32_e32 v55, 1.0, v55
	v_div_scale_f32 v58, s[86:87], v55, v55, 1.0
	v_rcp_f32_e32 v59, v58
	v_div_scale_f32 v60, vcc, 1.0, v55, 1.0
	v_fma_f32 v61, -v58, v59, 1.0
	v_fmac_f32_e32 v59, v61, v59
	v_mul_f32_e32 v61, v60, v59
	v_fma_f32 v62, -v58, v61, v60
	v_fmac_f32_e32 v61, v62, v59
	v_fma_f32 v58, -v58, v61, v60
	v_div_fmas_f32 v58, v58, v59, v61
	v_div_fixup_f32 v55, v58, v55, 1.0
	global_store_dword v[52:53], v55, off offset:12

.LBB0_790:
	s_nop 1
	v_mov_b32_e32 v34, v225
	v_add_u32_e32 v40, 0xa0, v172
	s_and_b64 vcc, exec, s[10:11]
	v_ashrrev_i32_e32 v41, 31, v40
	v_fmamk_f32 v34, v34, 0x3a800000, v155
	v_rsq_f32_e32 v38, v34
	s_cbranch_vccnz .LBB0_846
	s_and_b64 vcc, exec, s[8:9]
	s_mov_b64 s[12:13], -1
	s_cbranch_vccnz .LBB0_807
	s_andn2_b64 vcc, exec, s[84:85]
	s_cbranch_vccnz .LBB0_800
	s_andn2_b64 vcc, exec, s[34:35]
	s_cbranch_vccnz .LBB0_799
	v_readlane_b32 s12, v254, 58
	v_readlane_b32 s13, v254, 59
	v_readlane_b32 s44, v255, 0
	v_readlane_b32 s45, v255, 1
	v_mov_b64_e32 v[34:35], s[12:13]
	s_movk_i32 s12, 0x90
	v_mad_i64_i32 v[34:35], s[12:13], v40, s12, v[34:35]
	s_and_saveexec_b64 s[12:13], s[44:45]
	s_cbranch_execz .LBB0_796
	v_mov_b32_e32 v36, v246
	v_lshlrev_b32_e32 v142, 2, v146
	v_fmac_f32_e32 v36, v30, v38
	v_mul_f32_e32 v36, 0xbfb8aa3b, v36
	v_exp_f32_e32 v36, v36
	s_nop 0
	v_add_f32_e32 v39, 1.0, v36
	v_div_scale_f32 v42, s[86:87], v39, v39, 1.0
	v_rcp_f32_e32 v43, v42
	v_div_scale_f32 v44, vcc, 1.0, v39, 1.0
	v_lshl_add_u64 v[36:37], v[34:35], 0, v[142:143]
	v_fma_f32 v45, -v42, v43, 1.0
	v_fmac_f32_e32 v43, v45, v43
	v_mul_f32_e32 v45, v44, v43
	v_fma_f32 v46, -v42, v45, v44
	v_fmac_f32_e32 v45, v46, v43
	v_fma_f32 v42, -v42, v45, v44
	v_div_fmas_f32 v42, v42, v43, v45
	v_div_fixup_f32 v39, v42, v39, 1.0
	global_store_dword v[36:37], v39, off
	v_mov_b32_e32 v39, v247
	v_fmac_f32_e32 v39, v31, v38
	v_mul_f32_e32 v39, 0xbfb8aa3b, v39
	v_exp_f32_e32 v39, v39
	s_nop 0
	v_add_f32_e32 v39, 1.0, v39
	v_div_scale_f32 v42, s[86:87], v39, v39, 1.0
	v_rcp_f32_e32 v43, v42
	v_div_scale_f32 v44, vcc, 1.0, v39, 1.0
	v_fma_f32 v45, -v42, v43, 1.0
	v_fmac_f32_e32 v43, v45, v43
	v_mul_f32_e32 v45, v44, v43
	v_fma_f32 v46, -v42, v45, v44
	v_fmac_f32_e32 v45, v46, v43
	v_fma_f32 v42, -v42, v45, v44
	v_div_fmas_f32 v42, v42, v43, v45
	v_div_fixup_f32 v39, v42, v39, 1.0
	global_store_dword v[36:37], v39, off offset:4
	v_mov_b32_e32 v39, v248
	v_fmac_f32_e32 v39, v32, v38
	v_mul_f32_e32 v39, 0xbfb8aa3b, v39
	v_exp_f32_e32 v39, v39
	s_nop 0
	v_add_f32_e32 v39, 1.0, v39
	v_div_scale_f32 v42, s[86:87], v39, v39, 1.0
	v_rcp_f32_e32 v43, v42
	v_div_scale_f32 v44, vcc, 1.0, v39, 1.0
	v_fma_f32 v45, -v42, v43, 1.0
	v_fmac_f32_e32 v43, v45, v43
	v_mul_f32_e32 v45, v44, v43
	v_fma_f32 v46, -v42, v45, v44
	v_fmac_f32_e32 v45, v46, v43
	v_fma_f32 v42, -v42, v45, v44
	v_div_fmas_f32 v42, v42, v43, v45
	v_div_fixup_f32 v39, v42, v39, 1.0
	global_store_dword v[36:37], v39, off offset:8
	v_mov_b32_e32 v39, v249
	v_fmac_f32_e32 v39, v33, v38
	v_mul_f32_e32 v39, 0xbfb8aa3b, v39
	v_exp_f32_e32 v39, v39
	s_nop 0
	v_add_f32_e32 v39, 1.0, v39
	v_div_scale_f32 v42, s[86:87], v39, v39, 1.0
	v_rcp_f32_e32 v43, v42
	v_div_scale_f32 v44, vcc, 1.0, v39, 1.0
	v_fma_f32 v45, -v42, v43, 1.0
	v_fmac_f32_e32 v43, v45, v43
	v_mul_f32_e32 v45, v44, v43
	v_fma_f32 v46, -v42, v45, v44
	v_fmac_f32_e32 v45, v46, v43
	v_fma_f32 v42, -v42, v45, v44
	v_div_fmas_f32 v42, v42, v43, v45
	v_div_fixup_f32 v39, v42, v39, 1.0
	global_store_dword v[36:37], v39, off offset:12

.LBB0_814:
	s_nop 1
	v_mov_b32_e32 v18, v226
	v_add_u32_e32 v24, 0xb0, v172
	s_and_b64 vcc, exec, s[10:11]
	v_ashrrev_i32_e32 v25, 31, v24
	v_fmamk_f32 v18, v18, 0x3a800000, v155
	v_rsq_f32_e32 v22, v18
	s_cbranch_vccnz .LBB0_847
	s_and_b64 vcc, exec, s[8:9]
	s_mov_b64 s[8:9], -1
	s_cbranch_vccnz .LBB0_831
	s_andn2_b64 vcc, exec, s[84:85]
	s_cbranch_vccnz .LBB0_824
	s_andn2_b64 vcc, exec, s[34:35]
	s_cbranch_vccnz .LBB0_823
	v_readlane_b32 s8, v254, 58
	v_readlane_b32 s9, v254, 59
	v_lshlrev_b32_e32 v142, 2, v146
	s_nop 0
	v_mov_b64_e32 v[18:19], s[8:9]
	s_movk_i32 s8, 0x90
	v_mad_i64_i32 v[18:19], s[8:9], v24, s8, v[18:19]
	s_mov_b64 s[8:9], exec
	v_readlane_b32 s10, v255, 0
	v_readlane_b32 s11, v255, 1
	s_and_b64 s[10:11], s[8:9], s[10:11]
	s_mov_b64 exec, s[10:11]
	s_cbranch_execz .LBB0_820
	v_mov_b32_e32 v20, v246
	v_fmac_f32_e32 v20, v14, v22
	v_mul_f32_e32 v20, 0xbfb8aa3b, v20
	v_exp_f32_e32 v20, v20
	s_nop 0
	v_add_f32_e32 v23, 1.0, v20
	v_div_scale_f32 v26, s[10:11], v23, v23, 1.0
	v_rcp_f32_e32 v27, v26
	v_div_scale_f32 v28, vcc, 1.0, v23, 1.0
	v_lshl_add_u64 v[20:21], v[18:19], 0, v[142:143]
	v_fma_f32 v29, -v26, v27, 1.0
	v_fmac_f32_e32 v27, v29, v27
	v_mul_f32_e32 v29, v28, v27
	v_fma_f32 v30, -v26, v29, v28
	v_fmac_f32_e32 v29, v30, v27
	v_fma_f32 v26, -v26, v29, v28
	v_div_fmas_f32 v26, v26, v27, v29
	v_div_fixup_f32 v23, v26, v23, 1.0
	global_store_dword v[20:21], v23, off
	v_mov_b32_e32 v23, v247
	v_fmac_f32_e32 v23, v15, v22
	v_mul_f32_e32 v23, 0xbfb8aa3b, v23
	v_exp_f32_e32 v23, v23
	s_nop 0
	v_add_f32_e32 v23, 1.0, v23
	v_div_scale_f32 v26, s[10:11], v23, v23, 1.0
	v_rcp_f32_e32 v27, v26
	v_div_scale_f32 v28, vcc, 1.0, v23, 1.0
	v_fma_f32 v29, -v26, v27, 1.0
	v_fmac_f32_e32 v27, v29, v27
	v_mul_f32_e32 v29, v28, v27
	v_fma_f32 v30, -v26, v29, v28
	v_fmac_f32_e32 v29, v30, v27
	v_fma_f32 v26, -v26, v29, v28
	v_div_fmas_f32 v26, v26, v27, v29
	v_div_fixup_f32 v23, v26, v23, 1.0
	global_store_dword v[20:21], v23, off offset:4
	v_mov_b32_e32 v23, v248
	v_fmac_f32_e32 v23, v16, v22
	v_mul_f32_e32 v23, 0xbfb8aa3b, v23
	v_exp_f32_e32 v23, v23
	s_nop 0
	v_add_f32_e32 v23, 1.0, v23
	v_div_scale_f32 v26, s[10:11], v23, v23, 1.0
	v_rcp_f32_e32 v27, v26
	v_div_scale_f32 v28, vcc, 1.0, v23, 1.0
	v_fma_f32 v29, -v26, v27, 1.0
	v_fmac_f32_e32 v27, v29, v27
	v_mul_f32_e32 v29, v28, v27
	v_fma_f32 v30, -v26, v29, v28
	v_fmac_f32_e32 v29, v30, v27
	v_fma_f32 v26, -v26, v29, v28
	v_div_fmas_f32 v26, v26, v27, v29
	v_div_fixup_f32 v23, v26, v23, 1.0
	global_store_dword v[20:21], v23, off offset:8
	v_mov_b32_e32 v23, v249
	v_fmac_f32_e32 v23, v17, v22
	v_mul_f32_e32 v23, 0xbfb8aa3b, v23
	v_exp_f32_e32 v23, v23
	s_nop 0
	v_add_f32_e32 v23, 1.0, v23
	v_div_scale_f32 v26, s[10:11], v23, v23, 1.0
	v_rcp_f32_e32 v27, v26
	v_div_scale_f32 v28, vcc, 1.0, v23, 1.0
	v_fma_f32 v29, -v26, v27, 1.0
	v_fmac_f32_e32 v27, v29, v27
	v_mul_f32_e32 v29, v28, v27
	v_fma_f32 v30, -v26, v29, v28
	v_fmac_f32_e32 v29, v30, v27
	v_fma_f32 v26, -v26, v29, v28
	v_div_fmas_f32 v26, v26, v27, v29
	v_div_fixup_f32 v23, v26, v23, 1.0
	global_store_dword v[20:21], v23, off offset:12
